# FF1 epilogue stores of the 512 MB hidden activation marked nt (non-temporal) so they do not displace the re-read A/B panels from L2
# baseline (speedup 1.0000x reference)
;     __device__ __forceinline__ void operator()(const f32x4 (&acc)[2][2][4][2], const Unit& u, int wr, int wc, int fr, int fq) const {
;     ...
;                     if (4 * fq < rs_n) part[ai][m] = *(const f32x4*)(rs + (size_t)(row0 + ai * HALF + m * 16) * rs_ld + rs_off + 4 * fq);
;                 }
; #pragma unroll
;             for (int ai = 0; ai < 2; ++ai)
; #pragma unroll
;                 for (int m = 0; m < 4; ++m) {
;                     float t = (part[ai][m][0] + part[ai][m][1]) + (part[ai][m][2] + part[ai][m][3]);
;                     t += __shfl_xor(t, 16); t += __shfl_xor(t, 32);
;                     rsc[ai][m] = __builtin_amdgcn_rsqf(t * rs_inv + EPS);
.LBB0_1234:
	v_lshl_add_u32 v174, s49, 8, v167
	v_ashrrev_i32_e32 v175, 31, v174
	v_lshlrev_b64 v[130:131], 6, v[174:175]
	v_lshl_add_u64 v[130:131], v[148:149], 0, v[130:131]
	global_load_dwordx4 v[178:181], v[130:131], off
	v_or_b32_e32 v168, 16, v174
	v_ashrrev_i32_e32 v169, 31, v168
	v_lshlrev_b64 v[130:131], 6, v[168:169]
	v_lshl_add_u64 v[130:131], v[148:149], 0, v[130:131]
	global_load_dwordx4 v[182:185], v[130:131], off
	v_or_b32_e32 v164, 32, v174
	v_ashrrev_i32_e32 v165, 31, v164
	v_lshlrev_b64 v[130:131], 6, v[164:165]
	v_lshl_add_u64 v[130:131], v[148:149], 0, v[130:131]
	global_load_dwordx4 v[186:189], v[130:131], off
	v_or_b32_e32 v162, 48, v174
	v_ashrrev_i32_e32 v163, 31, v162
	v_lshlrev_b64 v[130:131], 6, v[162:163]
	v_lshl_add_u64 v[130:131], v[148:149], 0, v[130:131]
	global_load_dwordx4 v[190:193], v[130:131], off
	v_add_u32_e32 v160, 0x80, v174
	v_ashrrev_i32_e32 v161, 31, v160
	v_lshlrev_b64 v[130:131], 6, v[160:161]
	v_lshl_add_u64 v[130:131], v[148:149], 0, v[130:131]
	global_load_dwordx4 v[196:199], v[130:131], off
	v_add_u32_e32 v158, 0x90, v174
	v_ashrrev_i32_e32 v159, 31, v158
	v_lshlrev_b64 v[130:131], 6, v[158:159]
	v_add_u32_e32 v156, 0xa0, v174
	v_lshl_add_u64 v[130:131], v[148:149], 0, v[130:131]
	v_ashrrev_i32_e32 v157, 31, v156
	global_load_dwordx4 v[138:141], v[130:131], off
	v_lshlrev_b64 v[130:131], 6, v[156:157]
	v_add_u32_e32 v154, 0xb0, v174
	v_lshl_add_u64 v[130:131], v[148:149], 0, v[130:131]
	v_ashrrev_i32_e32 v155, 31, v154
	global_load_dwordx4 v[134:137], v[130:131], off
	v_lshlrev_b64 v[130:131], 6, v[154:155]
	v_lshl_add_u64 v[130:131], v[148:149], 0, v[130:131]
	global_load_dwordx4 v[130:133], v[130:131], off
	s_mov_b64 s[16:17], -1
	s_andn2_b64 vcc, exec, s[0:1]
	s_waitcnt vmcnt(0)
	v_mov_b32_e32 v200, v179
	v_mov_b32_e32 v201, v180
	v_mov_b32_e32 v179, v181
	v_pk_add_f32 v[178:179], v[200:201], v[178:179]
	v_mov_b32_e32 v180, v183
	v_add_f32_e32 v166, v178, v179
	ds_bpermute_b32 v170, v216, v166
	v_mov_b32_e32 v181, v184
	v_mov_b32_e32 v183, v185
	v_pk_add_f32 v[180:181], v[180:181], v[182:183]
	s_waitcnt lgkmcnt(0)
	v_add_f32_e32 v166, v166, v170
	ds_bpermute_b32 v170, v217, v166
	s_waitcnt lgkmcnt(0)
	v_add_f32_e32 v166, v166, v170
	v_fmamk_f32 v166, v166, 0x3a800000, v195
	v_rsq_f32_e32 v178, v166
	v_add_f32_e32 v166, v180, v181
	ds_bpermute_b32 v170, v216, v166
	v_mov_b32_e32 v180, v187
	v_mov_b32_e32 v181, v188
	v_mov_b32_e32 v187, v189
	v_pk_add_f32 v[180:181], v[180:181], v[186:187]
	s_waitcnt lgkmcnt(0)
	v_add_f32_e32 v166, v166, v170
	ds_bpermute_b32 v170, v217, v166
	s_waitcnt lgkmcnt(0)
	v_add_f32_e32 v166, v166, v170
	v_fmamk_f32 v166, v166, 0x3a800000, v195
	v_rsq_f32_e32 v176, v166
	v_add_f32_e32 v166, v180, v181
	ds_bpermute_b32 v170, v216, v166
	v_mov_b32_e32 v180, v191
	v_mov_b32_e32 v181, v192
	v_mov_b32_e32 v191, v193
	v_pk_add_f32 v[180:181], v[180:181], v[190:191]
	s_waitcnt lgkmcnt(0)
	v_add_f32_e32 v166, v166, v170
	ds_bpermute_b32 v170, v217, v166
	v_pk_mul_f32 v[106:107], v[106:107], v[176:177] op_sel_hi:[1,0]
	v_pk_mul_f32 v[112:113], v[112:113], v[176:177] op_sel_hi:[1,0]
	v_max_f32_e32 v106, 0, v106
	v_max_f32_e32 v107, 0, v107
	s_waitcnt lgkmcnt(0)
	v_add_f32_e32 v166, v166, v170
	v_fmamk_f32 v166, v166, 0x3a800000, v195
	v_rsq_f32_e32 v172, v166
	v_add_f32_e32 v166, v180, v181
	ds_bpermute_b32 v170, v216, v166
	v_mov_b32_e32 v180, v197
	v_mov_b32_e32 v181, v198
	v_mov_b32_e32 v197, v199
	v_pk_add_f32 v[180:181], v[180:181], v[196:197]
	s_waitcnt lgkmcnt(0)
	v_add_f32_e32 v166, v166, v170
	ds_bpermute_b32 v170, v217, v166
	v_pk_mul_f32 v[110:111], v[110:111], v[176:177] op_sel_hi:[1,0]
	v_pk_mul_f32 v[108:109], v[108:109], v[176:177] op_sel_hi:[1,0]
	v_max_f32_e32 v110, 0, v110
	v_max_f32_e32 v111, 0, v111
	s_waitcnt lgkmcnt(0)
	v_add_f32_e32 v166, v166, v170
	v_fmamk_f32 v166, v166, 0x3a800000, v195
	v_rsq_f32_e32 v170, v166
	v_add_f32_e32 v166, v180, v181
	ds_bpermute_b32 v179, v216, v166
	v_mov_b32_e32 v180, v139
	v_mov_b32_e32 v181, v140
	v_mov_b32_e32 v139, v141
	v_mov_b32_e32 v140, v135
	s_waitcnt lgkmcnt(0)
	v_add_f32_e32 v166, v166, v179
	ds_bpermute_b32 v179, v217, v166
	v_mov_b32_e32 v141, v136
	v_mov_b32_e32 v135, v137
	v_mov_b32_e32 v136, v131
	v_mov_b32_e32 v137, v132
	s_waitcnt lgkmcnt(0)
;     __device__ __forceinline__ void operator()(const f32x4 (&acc)[2][2][4][2], const Unit& u, int wr, int wc, int fr, int fq) const {
;     ...
;                     float t = (part[ai][m][0] + part[ai][m][1]) + (part[ai][m][2] + part[ai][m][3]);
;                     t += __shfl_xor(t, 16); t += __shfl_xor(t, 32);
;                     rsc[ai][m] = __builtin_amdgcn_rsqf(t * rs_inv + EPS);
;     ...
;                     f32x4 v0 = acc[ai][bj][m][0] * rs1, v1 = acc[ai][bj][m][1] * rs1;
;                     if (mode == EP_PLAIN) { store8(O + (size_t)row * ldc + col8, v0, v1); }
;                     else if (mode == EP_RELU2) {
; #pragma unroll
;                         for (int e = 0; e < 4; ++e) { float a = fmaxf(v0[e], 0.f), b = fmaxf(v1[e], 0.f); v0[e] = a * a; v1[e] = b * b; }
;                         store8(O + (size_t)row * ldc + col8, v0, v1);
	v_pk_mul_f32 v[122:123], v[122:123], v[178:179] op_sel_hi:[1,0]
	v_mov_b32_e32 v131, v133
	v_pk_mul_f32 v[128:129], v[128:129], v[178:179] op_sel_hi:[1,0]
	v_max_f32_e32 v122, 0, v122
	v_max_f32_e32 v123, 0, v123
	v_pk_add_f32 v[130:131], v[136:137], v[130:131]
	v_lshl_or_b32 v132, s48, 8, v173
	v_pk_mul_f32 v[126:127], v[126:127], v[178:179] op_sel_hi:[1,0]
	v_pk_mul_f32 v[124:125], v[124:125], v[178:179] op_sel_hi:[1,0]
	v_pk_mul_f32 v[136:137], v[122:123], v[122:123]
	v_max_f32_e32 v122, 0, v128
	v_max_f32_e32 v123, 0, v129
	v_max_f32_e32 v126, 0, v126
	v_max_f32_e32 v127, 0, v127
	v_max_f32_e32 v124, 0, v124
	v_max_f32_e32 v125, 0, v125
	v_pk_mul_f32 v[128:129], v[122:123], v[122:123]
	v_lshlrev_b64 v[122:123], 13, v[174:175]
	v_ashrrev_i32_e32 v133, 31, v132
	v_pk_add_f32 v[134:135], v[140:141], v[134:135]
	v_pk_mul_f32 v[126:127], v[126:127], v[126:127]
	v_pk_mul_f32 v[140:141], v[124:125], v[124:125]
	v_lshl_add_u64 v[124:125], s[6:7], 0, v[122:123]
	v_lshlrev_b64 v[122:123], 1, v[132:133]
	v_pk_mul_f32 v[114:115], v[114:115], v[178:179] op_sel_hi:[1,0]
	v_lshl_add_u64 v[132:133], v[124:125], 0, v[122:123]
	v_cvt_pk_bf16_f32 v124, v126, v127
	v_cvt_pk_bf16_f32 v125, v128, v129
	v_cvt_pk_bf16_f32 v126, v136, v137
	v_cvt_pk_bf16_f32 v127, v140, v141
	v_pk_mul_f32 v[120:121], v[120:121], v[178:179] op_sel_hi:[1,0]
	v_pk_mul_f32 v[118:119], v[118:119], v[178:179] op_sel_hi:[1,0]
	v_pk_mul_f32 v[116:117], v[116:117], v[178:179] op_sel_hi:[1,0]
	v_max_f32_e32 v114, 0, v114
	v_max_f32_e32 v115, 0, v115
	global_store_dwordx4 v[132:133], v[124:127], off nt
	v_max_f32_e32 v118, 0, v118
	v_max_f32_e32 v119, 0, v119
	v_pk_mul_f32 v[124:125], v[114:115], v[114:115]
	v_max_f32_e32 v114, 0, v120
	v_max_f32_e32 v116, 0, v116
	v_max_f32_e32 v115, 0, v121
	v_max_f32_e32 v117, 0, v117
	v_pk_mul_f32 v[118:119], v[118:119], v[118:119]
	v_pk_mul_f32 v[120:121], v[114:115], v[114:115]
	v_pk_mul_f32 v[126:127], v[116:117], v[116:117]
	v_cvt_pk_bf16_f32 v114, v118, v119
	v_cvt_pk_bf16_f32 v115, v120, v121
	v_cvt_pk_bf16_f32 v116, v124, v125
	v_cvt_pk_bf16_f32 v117, v126, v127
	global_store_dwordx4 v[132:133], v[114:117], off offset:256 nt
	v_max_f32_e32 v108, 0, v108
	v_max_f32_e32 v109, 0, v109
	v_pk_mul_f32 v[114:115], v[106:107], v[106:107]
	v_max_f32_e32 v106, 0, v112
	v_max_f32_e32 v107, 0, v113
	v_pk_mul_f32 v[112:113], v[106:107], v[106:107]
	v_lshlrev_b64 v[106:107], 13, v[168:169]
	v_pk_mul_f32 v[110:111], v[110:111], v[110:111]
	v_pk_mul_f32 v[116:117], v[108:109], v[108:109]
	v_lshl_add_u64 v[106:107], s[6:7], 0, v[106:107]
	v_pk_mul_f32 v[98:99], v[98:99], v[176:177] op_sel_hi:[1,0]
	v_lshl_add_u64 v[118:119], v[106:107], 0, v[122:123]
	v_cvt_pk_bf16_f32 v106, v110, v111
	v_cvt_pk_bf16_f32 v107, v112, v113
	v_cvt_pk_bf16_f32 v108, v114, v115
	v_cvt_pk_bf16_f32 v109, v116, v117
	v_pk_mul_f32 v[104:105], v[104:105], v[176:177] op_sel_hi:[1,0]
	v_pk_mul_f32 v[102:103], v[102:103], v[176:177] op_sel_hi:[1,0]
	v_pk_mul_f32 v[100:101], v[100:101], v[176:177] op_sel_hi:[1,0]
	v_max_f32_e32 v98, 0, v98
	v_max_f32_e32 v99, 0, v99
	global_store_dwordx4 v[118:119], v[106:109], off nt
	v_max_f32_e32 v102, 0, v102
	v_max_f32_e32 v103, 0, v103
	v_pk_mul_f32 v[106:107], v[98:99], v[98:99]
	v_max_f32_e32 v98, 0, v104
	v_max_f32_e32 v100, 0, v100
	v_max_f32_e32 v99, 0, v105
	v_max_f32_e32 v101, 0, v101
	v_pk_mul_f32 v[102:103], v[102:103], v[102:103]
	v_pk_mul_f32 v[104:105], v[98:99], v[98:99]
	v_pk_mul_f32 v[108:109], v[100:101], v[100:101]
	v_pk_mul_f32 v[90:91], v[90:91], v[172:173] op_sel_hi:[1,0]
	v_pk_add_f32 v[138:139], v[180:181], v[138:139]
	v_cvt_pk_bf16_f32 v98, v102, v103
	v_cvt_pk_bf16_f32 v99, v104, v105
	v_cvt_pk_bf16_f32 v100, v106, v107
	v_cvt_pk_bf16_f32 v101, v108, v109
	v_pk_mul_f32 v[96:97], v[96:97], v[172:173] op_sel_hi:[1,0]
	v_pk_mul_f32 v[94:95], v[94:95], v[172:173] op_sel_hi:[1,0]
	v_pk_mul_f32 v[92:93], v[92:93], v[172:173] op_sel_hi:[1,0]
	v_max_f32_e32 v90, 0, v90
	v_max_f32_e32 v91, 0, v91
	v_add_f32_e32 v138, v138, v139
	global_store_dwordx4 v[118:119], v[98:101], off offset:256 nt
	v_max_f32_e32 v94, 0, v94
	v_max_f32_e32 v95, 0, v95
	v_lshlrev_b64 v[98:99], 13, v[164:165]
	v_pk_mul_f32 v[100:101], v[90:91], v[90:91]
	v_max_f32_e32 v90, 0, v96
	v_max_f32_e32 v92, 0, v92
	v_max_f32_e32 v91, 0, v97
	v_max_f32_e32 v93, 0, v93
	ds_bpermute_b32 v139, v216, v138
	v_pk_mul_f32 v[94:95], v[94:95], v[94:95]
	v_pk_mul_f32 v[96:97], v[90:91], v[90:91]
	v_pk_mul_f32 v[102:103], v[92:93], v[92:93]
	v_lshl_add_u64 v[90:91], s[6:7], 0, v[98:99]
	v_pk_mul_f32 v[82:83], v[82:83], v[172:173] op_sel_hi:[1,0]
	v_lshl_add_u64 v[98:99], v[90:91], 0, v[122:123]
	v_cvt_pk_bf16_f32 v90, v94, v95
	v_cvt_pk_bf16_f32 v91, v96, v97
	v_cvt_pk_bf16_f32 v92, v100, v101
	v_cvt_pk_bf16_f32 v93, v102, v103
	v_pk_mul_f32 v[88:89], v[88:89], v[172:173] op_sel_hi:[1,0]
	v_pk_mul_f32 v[86:87], v[86:87], v[172:173] op_sel_hi:[1,0]
	v_pk_mul_f32 v[84:85], v[84:85], v[172:173] op_sel_hi:[1,0]
	v_max_f32_e32 v82, 0, v82
	v_max_f32_e32 v83, 0, v83
	global_store_dwordx4 v[98:99], v[90:93], off nt
	v_max_f32_e32 v86, 0, v86
	v_max_f32_e32 v87, 0, v87
	v_pk_mul_f32 v[90:91], v[82:83], v[82:83]
	v_max_f32_e32 v82, 0, v88
	v_max_f32_e32 v84, 0, v84
	v_max_f32_e32 v83, 0, v89
	v_max_f32_e32 v85, 0, v85
	v_pk_mul_f32 v[86:87], v[86:87], v[86:87]
	v_pk_mul_f32 v[88:89], v[82:83], v[82:83]
	v_pk_mul_f32 v[92:93], v[84:85], v[84:85]
	v_pk_mul_f32 v[74:75], v[74:75], v[170:171] op_sel_hi:[1,0]
	v_add_f32_e32 v166, v166, v179
	v_cvt_pk_bf16_f32 v82, v86, v87
	v_cvt_pk_bf16_f32 v83, v88, v89
	v_cvt_pk_bf16_f32 v84, v90, v91
	v_cvt_pk_bf16_f32 v85, v92, v93
	v_pk_mul_f32 v[80:81], v[80:81], v[170:171] op_sel_hi:[1,0]
	v_max_f32_e32 v74, 0, v74
	v_max_f32_e32 v75, 0, v75
	v_fmamk_f32 v166, v166, 0x3a800000, v195
	s_waitcnt lgkmcnt(0)
;     __device__ __forceinline__ void operator()(const f32x4 (&acc)[2][2][4][2], const Unit& u, int wr, int wc, int fr, int fq) const {
;     ...
;                     float t = (part[ai][m][0] + part[ai][m][1]) + (part[ai][m][2] + part[ai][m][3]);
;                     t += __shfl_xor(t, 16); t += __shfl_xor(t, 32);
;                     rsc[ai][m] = __builtin_amdgcn_rsqf(t * rs_inv + EPS);
;     ...
;                     f32x4 v0 = acc[ai][bj][m][0] * rs1, v1 = acc[ai][bj][m][1] * rs1;
;                     if (mode == EP_PLAIN) { store8(O + (size_t)row * ldc + col8, v0, v1); }
;                     else if (mode == EP_RELU2) {
; #pragma unroll
;                         for (int e = 0; e < 4; ++e) { float a = fmaxf(v0[e], 0.f), b = fmaxf(v1[e], 0.f); v0[e] = a * a; v1[e] = b * b; }
;                         store8(O + (size_t)row * ldc + col8, v0, v1);
	v_add_f32_e32 v138, v138, v139
	global_store_dwordx4 v[98:99], v[82:85], off offset:256 nt
	v_pk_mul_f32 v[78:79], v[78:79], v[170:171] op_sel_hi:[1,0]
	v_pk_mul_f32 v[76:77], v[76:77], v[170:171] op_sel_hi:[1,0]
	v_pk_mul_f32 v[82:83], v[74:75], v[74:75]
	v_max_f32_e32 v74, 0, v80
	v_max_f32_e32 v75, 0, v81
	v_rsq_f32_e32 v166, v166
	ds_bpermute_b32 v139, v217, v138
	v_add_f32_e32 v134, v134, v135
	v_max_f32_e32 v78, 0, v78
	v_max_f32_e32 v79, 0, v79
	v_max_f32_e32 v76, 0, v76
	v_max_f32_e32 v77, 0, v77
	v_pk_mul_f32 v[80:81], v[74:75], v[74:75]
	v_lshlrev_b64 v[74:75], 13, v[162:163]
	ds_bpermute_b32 v135, v216, v134
	v_pk_mul_f32 v[78:79], v[78:79], v[78:79]
	v_pk_mul_f32 v[84:85], v[76:77], v[76:77]
	v_lshl_add_u64 v[74:75], s[6:7], 0, v[74:75]
	v_pk_mul_f32 v[66:67], v[66:67], v[170:171] op_sel_hi:[1,0]
	v_lshl_add_u64 v[86:87], v[74:75], 0, v[122:123]
	v_cvt_pk_bf16_f32 v74, v78, v79
	v_cvt_pk_bf16_f32 v75, v80, v81
	v_cvt_pk_bf16_f32 v76, v82, v83
	v_cvt_pk_bf16_f32 v77, v84, v85
	v_pk_mul_f32 v[72:73], v[72:73], v[170:171] op_sel_hi:[1,0]
	v_pk_mul_f32 v[70:71], v[70:71], v[170:171] op_sel_hi:[1,0]
	v_pk_mul_f32 v[68:69], v[68:69], v[170:171] op_sel_hi:[1,0]
	v_max_f32_e32 v66, 0, v66
	v_max_f32_e32 v67, 0, v67
	global_store_dwordx4 v[86:87], v[74:77], off nt
	v_max_f32_e32 v70, 0, v70
	v_max_f32_e32 v71, 0, v71
	v_pk_mul_f32 v[74:75], v[66:67], v[66:67]
	v_max_f32_e32 v66, 0, v72
	v_max_f32_e32 v68, 0, v68
	v_max_f32_e32 v67, 0, v73
	v_max_f32_e32 v69, 0, v69
	v_pk_mul_f32 v[70:71], v[70:71], v[70:71]
	v_pk_mul_f32 v[72:73], v[66:67], v[66:67]
	v_pk_mul_f32 v[76:77], v[68:69], v[68:69]
	v_pk_mul_f32 v[58:59], v[58:59], v[166:167] op_sel_hi:[1,0]
	s_waitcnt lgkmcnt(1)
	v_add_f32_e32 v138, v138, v139
	v_cvt_pk_bf16_f32 v66, v70, v71
	v_cvt_pk_bf16_f32 v67, v72, v73
	v_cvt_pk_bf16_f32 v68, v74, v75
	v_cvt_pk_bf16_f32 v69, v76, v77
	v_pk_mul_f32 v[64:65], v[64:65], v[166:167] op_sel_hi:[1,0]
	v_max_f32_e32 v58, 0, v58
	v_max_f32_e32 v59, 0, v59
	v_fmamk_f32 v138, v138, 0x3a800000, v195
	s_waitcnt lgkmcnt(0)
	v_add_f32_e32 v134, v134, v135
	v_add_f32_e32 v130, v130, v131
	global_store_dwordx4 v[86:87], v[66:69], off offset:256 nt
	v_pk_mul_f32 v[62:63], v[62:63], v[166:167] op_sel_hi:[1,0]
	v_pk_mul_f32 v[60:61], v[60:61], v[166:167] op_sel_hi:[1,0]
	v_pk_mul_f32 v[66:67], v[58:59], v[58:59]
	v_max_f32_e32 v58, 0, v64
	v_max_f32_e32 v59, 0, v65
	v_rsq_f32_e32 v138, v138
	ds_bpermute_b32 v135, v217, v134
	ds_bpermute_b32 v131, v216, v130
	v_max_f32_e32 v62, 0, v62
	v_max_f32_e32 v63, 0, v63
	v_max_f32_e32 v60, 0, v60
	v_max_f32_e32 v61, 0, v61
	v_pk_mul_f32 v[64:65], v[58:59], v[58:59]
	v_lshlrev_b64 v[58:59], 13, v[160:161]
	v_pk_mul_f32 v[62:63], v[62:63], v[62:63]
	v_pk_mul_f32 v[68:69], v[60:61], v[60:61]
	v_lshl_add_u64 v[58:59], s[6:7], 0, v[58:59]
	v_pk_mul_f32 v[50:51], v[50:51], v[166:167] op_sel_hi:[1,0]
	v_lshl_add_u64 v[70:71], v[58:59], 0, v[122:123]
	v_cvt_pk_bf16_f32 v58, v62, v63
	v_cvt_pk_bf16_f32 v59, v64, v65
	v_cvt_pk_bf16_f32 v60, v66, v67
	v_cvt_pk_bf16_f32 v61, v68, v69
	v_pk_mul_f32 v[56:57], v[56:57], v[166:167] op_sel_hi:[1,0]
	v_pk_mul_f32 v[54:55], v[54:55], v[166:167] op_sel_hi:[1,0]
	v_pk_mul_f32 v[52:53], v[52:53], v[166:167] op_sel_hi:[1,0]
	v_max_f32_e32 v50, 0, v50
	v_max_f32_e32 v51, 0, v51
	global_store_dwordx4 v[70:71], v[58:61], off nt
	v_max_f32_e32 v54, 0, v54
	v_max_f32_e32 v55, 0, v55
	v_pk_mul_f32 v[58:59], v[50:51], v[50:51]
	v_max_f32_e32 v50, 0, v56
	v_max_f32_e32 v52, 0, v52
	v_max_f32_e32 v51, 0, v57
	v_max_f32_e32 v53, 0, v53
	v_pk_mul_f32 v[54:55], v[54:55], v[54:55]
	v_pk_mul_f32 v[56:57], v[50:51], v[50:51]
	v_pk_mul_f32 v[60:61], v[52:53], v[52:53]
	v_pk_mul_f32 v[42:43], v[42:43], v[138:139] op_sel_hi:[1,0]
	s_waitcnt lgkmcnt(1)
	v_add_f32_e32 v134, v134, v135
	s_waitcnt lgkmcnt(0)
	v_add_f32_e32 v130, v130, v131
	v_cvt_pk_bf16_f32 v50, v54, v55
	v_cvt_pk_bf16_f32 v51, v56, v57
	v_cvt_pk_bf16_f32 v52, v58, v59
	v_cvt_pk_bf16_f32 v53, v60, v61
	v_pk_mul_f32 v[48:49], v[48:49], v[138:139] op_sel_hi:[1,0]
	v_max_f32_e32 v42, 0, v42
	v_max_f32_e32 v43, 0, v43
	v_fmamk_f32 v134, v134, 0x3a800000, v195
	ds_bpermute_b32 v131, v217, v130
	global_store_dwordx4 v[70:71], v[50:53], off offset:256 nt
	v_pk_mul_f32 v[46:47], v[46:47], v[138:139] op_sel_hi:[1,0]
	v_pk_mul_f32 v[44:45], v[44:45], v[138:139] op_sel_hi:[1,0]
	v_pk_mul_f32 v[50:51], v[42:43], v[42:43]
	v_max_f32_e32 v42, 0, v48
	v_max_f32_e32 v43, 0, v49
	v_rsq_f32_e32 v134, v134
	v_max_f32_e32 v46, 0, v46
	v_max_f32_e32 v47, 0, v47
	v_max_f32_e32 v44, 0, v44
	v_max_f32_e32 v45, 0, v45
	v_pk_mul_f32 v[48:49], v[42:43], v[42:43]
	v_lshlrev_b64 v[42:43], 13, v[158:159]
	v_pk_mul_f32 v[46:47], v[46:47], v[46:47]
	v_pk_mul_f32 v[52:53], v[44:45], v[44:45]
	v_lshl_add_u64 v[42:43], s[6:7], 0, v[42:43]
	v_pk_mul_f32 v[34:35], v[34:35], v[138:139] op_sel_hi:[1,0]
	v_lshl_add_u64 v[54:55], v[42:43], 0, v[122:123]
	v_cvt_pk_bf16_f32 v42, v46, v47
	v_cvt_pk_bf16_f32 v43, v48, v49
	v_cvt_pk_bf16_f32 v44, v50, v51
	v_cvt_pk_bf16_f32 v45, v52, v53
	v_pk_mul_f32 v[40:41], v[40:41], v[138:139] op_sel_hi:[1,0]
	v_pk_mul_f32 v[38:39], v[38:39], v[138:139] op_sel_hi:[1,0]
	v_pk_mul_f32 v[36:37], v[36:37], v[138:139] op_sel_hi:[1,0]
	v_max_f32_e32 v34, 0, v34
	v_max_f32_e32 v35, 0, v35
	global_store_dwordx4 v[54:55], v[42:45], off nt
	v_max_f32_e32 v38, 0, v38
	v_max_f32_e32 v39, 0, v39
	v_pk_mul_f32 v[42:43], v[34:35], v[34:35]
	v_max_f32_e32 v34, 0, v40
	v_max_f32_e32 v36, 0, v36
	v_max_f32_e32 v35, 0, v41
	v_max_f32_e32 v37, 0, v37
	s_waitcnt lgkmcnt(0)
; #define PG8_BAR __builtin_amdgcn_s_barrier()
;     __device__ __forceinline__ void operator()(const f32x4 (&acc)[2][2][4][2], const Unit& u, int wr, int wc, int fr, int fq) const {
;     ...
;                     f32x4 v0 = acc[ai][bj][m][0] * rs1, v1 = acc[ai][bj][m][1] * rs1;
;                     if (mode == EP_PLAIN) { store8(O + (size_t)row * ldc + col8, v0, v1); }
;                     else if (mode == EP_RELU2) {
; #pragma unroll
;                         for (int e = 0; e < 4; ++e) { float a = fmaxf(v0[e], 0.f), b = fmaxf(v1[e], 0.f); v0[e] = a * a; v1[e] = b * b; }
;                         store8(O + (size_t)row * ldc + col8, v0, v1);
; template <class Epi, class Sched, bool ALIGN_EPI = false, bool SP2 = false>
; __device__ __forceinline__ void gemm_phase(PG8_LAS unsigned char* lds, const Gemm g, const Sched& S, const Epi& E, int wv) {
;     ...
; #pragma unroll
;         for (int a = 0; a < 2; ++a)
; #pragma unroll
;             for (int b = 0; b < 2; ++b)
; #pragma unroll
;                 for (int m = 0; m < 4; ++m)
; #pragma unroll
;                     for (int n = 0; n < 2; ++n) acc[a][b][m][n] = (f32x4){0.f, 0.f, 0.f, 0.f};
;         cur = nxt; cA = nA; cB = nB; ++ui;
;         if constexpr (ALIGN_EPI) { if (wr == 1) PG8_BAR; }
	v_add_f32_e32 v130, v130, v131
	v_pk_mul_f32 v[38:39], v[38:39], v[38:39]
	v_pk_mul_f32 v[40:41], v[34:35], v[34:35]
	v_pk_mul_f32 v[44:45], v[36:37], v[36:37]
	v_pk_mul_f32 v[26:27], v[26:27], v[134:135] op_sel_hi:[1,0]
	v_fmamk_f32 v130, v130, 0x3a800000, v195
	v_cvt_pk_bf16_f32 v34, v38, v39
	v_cvt_pk_bf16_f32 v35, v40, v41
	v_cvt_pk_bf16_f32 v36, v42, v43
	v_cvt_pk_bf16_f32 v37, v44, v45
	v_pk_mul_f32 v[32:33], v[32:33], v[134:135] op_sel_hi:[1,0]
	v_pk_mul_f32 v[30:31], v[30:31], v[134:135] op_sel_hi:[1,0]
	v_pk_mul_f32 v[28:29], v[28:29], v[134:135] op_sel_hi:[1,0]
	v_max_f32_e32 v26, 0, v26
	v_max_f32_e32 v27, 0, v27
	v_rsq_f32_e32 v130, v130
	global_store_dwordx4 v[54:55], v[34:37], off offset:256 nt
	v_max_f32_e32 v30, 0, v30
	v_max_f32_e32 v31, 0, v31
	v_lshlrev_b64 v[34:35], 13, v[156:157]
	v_pk_mul_f32 v[36:37], v[26:27], v[26:27]
	v_max_f32_e32 v26, 0, v32
	v_max_f32_e32 v28, 0, v28
	v_max_f32_e32 v27, 0, v33
	v_max_f32_e32 v29, 0, v29
	v_pk_mul_f32 v[30:31], v[30:31], v[30:31]
	v_pk_mul_f32 v[32:33], v[26:27], v[26:27]
	v_pk_mul_f32 v[38:39], v[28:29], v[28:29]
	v_lshl_add_u64 v[26:27], s[6:7], 0, v[34:35]
	v_pk_mul_f32 v[18:19], v[18:19], v[134:135] op_sel_hi:[1,0]
	v_lshl_add_u64 v[34:35], v[26:27], 0, v[122:123]
	v_cvt_pk_bf16_f32 v26, v30, v31
	v_cvt_pk_bf16_f32 v27, v32, v33
	v_cvt_pk_bf16_f32 v28, v36, v37
	v_cvt_pk_bf16_f32 v29, v38, v39
	v_pk_mul_f32 v[24:25], v[24:25], v[134:135] op_sel_hi:[1,0]
	v_pk_mul_f32 v[22:23], v[22:23], v[134:135] op_sel_hi:[1,0]
	v_pk_mul_f32 v[20:21], v[20:21], v[134:135] op_sel_hi:[1,0]
	v_max_f32_e32 v18, 0, v18
	v_max_f32_e32 v19, 0, v19
	global_store_dwordx4 v[34:35], v[26:29], off nt
	v_max_f32_e32 v22, 0, v22
	v_max_f32_e32 v23, 0, v23
	v_pk_mul_f32 v[26:27], v[18:19], v[18:19]
	v_max_f32_e32 v18, 0, v24
	v_max_f32_e32 v20, 0, v20
	v_max_f32_e32 v19, 0, v25
	v_max_f32_e32 v21, 0, v21
	v_pk_mul_f32 v[22:23], v[22:23], v[22:23]
	v_pk_mul_f32 v[24:25], v[18:19], v[18:19]
	v_pk_mul_f32 v[28:29], v[20:21], v[20:21]
	v_pk_mul_f32 v[10:11], v[10:11], v[130:131] op_sel_hi:[1,0]
	v_cvt_pk_bf16_f32 v18, v22, v23
	v_cvt_pk_bf16_f32 v19, v24, v25
	v_cvt_pk_bf16_f32 v20, v26, v27
	v_cvt_pk_bf16_f32 v21, v28, v29
	v_pk_mul_f32 v[16:17], v[16:17], v[130:131] op_sel_hi:[1,0]
	v_max_f32_e32 v10, 0, v10
	v_max_f32_e32 v11, 0, v11
	global_store_dwordx4 v[34:35], v[18:21], off offset:256 nt
	v_pk_mul_f32 v[14:15], v[14:15], v[130:131] op_sel_hi:[1,0]
	v_pk_mul_f32 v[12:13], v[12:13], v[130:131] op_sel_hi:[1,0]
	v_pk_mul_f32 v[18:19], v[10:11], v[10:11]
	v_max_f32_e32 v10, 0, v16
	v_max_f32_e32 v11, 0, v17
	v_max_f32_e32 v14, 0, v14
	v_max_f32_e32 v15, 0, v15
	v_max_f32_e32 v12, 0, v12
	v_max_f32_e32 v13, 0, v13
	v_pk_mul_f32 v[16:17], v[10:11], v[10:11]
	v_lshlrev_b64 v[10:11], 13, v[154:155]
	v_pk_mul_f32 v[14:15], v[14:15], v[14:15]
	v_pk_mul_f32 v[20:21], v[12:13], v[12:13]
	v_lshl_add_u64 v[10:11], s[6:7], 0, v[10:11]
	v_pk_mul_f32 v[2:3], v[2:3], v[130:131] op_sel_hi:[1,0]
	v_lshl_add_u64 v[22:23], v[10:11], 0, v[122:123]
	v_cvt_pk_bf16_f32 v10, v14, v15
	v_cvt_pk_bf16_f32 v11, v16, v17
	v_cvt_pk_bf16_f32 v12, v18, v19
	v_cvt_pk_bf16_f32 v13, v20, v21
	v_pk_mul_f32 v[8:9], v[8:9], v[130:131] op_sel_hi:[1,0]
	v_pk_mul_f32 v[6:7], v[6:7], v[130:131] op_sel_hi:[1,0]
	v_pk_mul_f32 v[4:5], v[4:5], v[130:131] op_sel_hi:[1,0]
	v_max_f32_e32 v2, 0, v2
	v_max_f32_e32 v3, 0, v3
	global_store_dwordx4 v[22:23], v[10:13], off nt
	v_max_f32_e32 v6, 0, v6
	v_max_f32_e32 v7, 0, v7
	v_pk_mul_f32 v[10:11], v[2:3], v[2:3]
	v_max_f32_e32 v2, 0, v8
	v_max_f32_e32 v4, 0, v4
	v_max_f32_e32 v3, 0, v9
	v_max_f32_e32 v5, 0, v5
	v_pk_mul_f32 v[6:7], v[6:7], v[6:7]
	v_pk_mul_f32 v[8:9], v[2:3], v[2:3]
	v_pk_mul_f32 v[12:13], v[4:5], v[4:5]
	v_cvt_pk_bf16_f32 v2, v6, v7
	v_cvt_pk_bf16_f32 v3, v8, v9
	v_cvt_pk_bf16_f32 v4, v10, v11
	v_cvt_pk_bf16_f32 v5, v12, v13
	global_store_dwordx4 v[22:23], v[2:5], off offset:256 nt
	s_cbranch_vccnz .LBB0_1227
	s_andn2_b64 vcc, exec, s[4:5]
	s_cbranch_vccnz .LBB0_1226
	s_barrier
	s_branch .LBB0_1226
